# swiglu epilogue packed math + sample-row finalize loads hoisted + norm gains preloaded
# baseline (speedup 1.0000x reference)
.LBB0_65:
	v_cmp_lt_i32_e64 s[0:1], s77, v136
	s_and_saveexec_b64 s[12:13], s[0:1]
	s_cbranch_execz .LBB0_64
	v_add_u32_e32 v6, 0xffffc000, v136
	s_waitcnt lgkmcnt(0)
	v_mov_b32_e32 v7, v137
	v_lshlrev_b64 v[6:7], 12, v[6:7]
	v_lshlrev_b64 v[4:5], 11, v[136:137]
	v_lshl_add_u64 v[24:25], v[2:3], 0, v[6:7]
	v_lshl_add_u64 v[4:5], v[0:1], 0, v[4:5]
	s_mov_b32 s34, 0x400000
	v_lshl_add_u64 v[26:27], v[24:25], 0, s[34:35]
	v_lshl_add_u64 v[28:29], v[26:27], 0, s[34:35]
	v_lshl_add_u64 v[30:31], v[28:29], 0, s[34:35]
	global_load_dwordx2 v[22:23], v[4:5], off
	global_load_dwordx2 v[32:33], v[4:5], off offset:512
	global_load_dwordx2 v[34:35], v[4:5], off offset:1024
	global_load_dwordx2 v[36:37], v[4:5], off offset:1536
	global_load_dwordx4 v[40:43], v[24:25], off
	global_load_dwordx4 v[44:47], v[26:27], off
	global_load_dwordx4 v[48:51], v[28:29], off
	global_load_dwordx4 v[52:55], v[30:31], off
	global_load_dwordx4 v[56:59], v[24:25], off offset:1024
	global_load_dwordx4 v[60:63], v[26:27], off offset:1024
	global_load_dwordx4 v[64:67], v[28:29], off offset:1024
	global_load_dwordx4 v[68:71], v[30:31], off offset:1024
	global_load_dwordx4 v[72:75], v[24:25], off offset:2048
	global_load_dwordx4 v[76:79], v[26:27], off offset:2048
	global_load_dwordx4 v[80:83], v[28:29], off offset:2048
	global_load_dwordx4 v[84:87], v[30:31], off offset:2048
	global_load_dwordx4 v[88:91], v[24:25], off offset:3072
	global_load_dwordx4 v[92:95], v[26:27], off offset:3072
	global_load_dwordx4 v[96:99], v[28:29], off offset:3072
	global_load_dwordx4 v[100:103], v[30:31], off offset:3072
	s_waitcnt vmcnt(12)
	v_lshlrev_b32_e32 v8, 16, v22
	v_and_b32_e32 v9, 0xffff0000, v22
	v_lshlrev_b32_e32 v10, 16, v23
	v_and_b32_e32 v11, 0xffff0000, v23
	v_pk_add_f32 v[8:9], v[40:41], v[8:9]
	v_pk_add_f32 v[10:11], v[42:43], v[10:11]
	v_pk_add_f32 v[8:9], v[44:45], v[8:9]
	v_pk_add_f32 v[10:11], v[46:47], v[10:11]
	v_pk_add_f32 v[8:9], v[48:49], v[8:9]
	v_pk_add_f32 v[10:11], v[50:51], v[10:11]
	v_pk_add_f32 v[8:9], v[52:53], v[8:9]
	v_pk_add_f32 v[10:11], v[54:55], v[10:11]
	v_mul_f32_e32 v6, v8, v8
	v_fmac_f32_e32 v6, v9, v9
	v_fmac_f32_e32 v6, v10, v10
	v_fmac_f32_e32 v6, v11, v11
	v_cvt_pk_bf16_f32 v14, v8, v9
	v_cvt_pk_bf16_f32 v15, v10, v11
	global_store_dwordx2 v[4:5], v[14:15], off
	s_waitcnt vmcnt(9)
	v_lshlrev_b32_e32 v8, 16, v32
	v_and_b32_e32 v9, 0xffff0000, v32
	v_lshlrev_b32_e32 v10, 16, v33
	v_and_b32_e32 v11, 0xffff0000, v33
	v_pk_add_f32 v[8:9], v[56:57], v[8:9]
	v_pk_add_f32 v[10:11], v[58:59], v[10:11]
	v_pk_add_f32 v[8:9], v[60:61], v[8:9]
	v_pk_add_f32 v[10:11], v[62:63], v[10:11]
	v_pk_add_f32 v[8:9], v[64:65], v[8:9]
	v_pk_add_f32 v[10:11], v[66:67], v[10:11]
	v_pk_add_f32 v[8:9], v[68:69], v[8:9]
	v_pk_add_f32 v[10:11], v[70:71], v[10:11]
	v_fmac_f32_e32 v6, v8, v8
	v_fmac_f32_e32 v6, v9, v9
	v_fmac_f32_e32 v6, v10, v10
	v_fmac_f32_e32 v6, v11, v11
	v_cvt_pk_bf16_f32 v16, v8, v9
	v_cvt_pk_bf16_f32 v17, v10, v11
	global_store_dwordx2 v[4:5], v[16:17], off offset:512
	s_waitcnt vmcnt(6)
	v_lshlrev_b32_e32 v8, 16, v34
	v_and_b32_e32 v9, 0xffff0000, v34
	v_lshlrev_b32_e32 v10, 16, v35
	v_and_b32_e32 v11, 0xffff0000, v35
	v_pk_add_f32 v[8:9], v[72:73], v[8:9]
	v_pk_add_f32 v[10:11], v[74:75], v[10:11]
	v_pk_add_f32 v[8:9], v[76:77], v[8:9]
	v_pk_add_f32 v[10:11], v[78:79], v[10:11]
	v_pk_add_f32 v[8:9], v[80:81], v[8:9]
	v_pk_add_f32 v[10:11], v[82:83], v[10:11]
	v_pk_add_f32 v[8:9], v[84:85], v[8:9]
	v_pk_add_f32 v[10:11], v[86:87], v[10:11]
	v_fmac_f32_e32 v6, v8, v8
	v_fmac_f32_e32 v6, v9, v9
	v_fmac_f32_e32 v6, v10, v10
	v_fmac_f32_e32 v6, v11, v11
	v_cvt_pk_bf16_f32 v18, v8, v9
	v_cvt_pk_bf16_f32 v19, v10, v11
	global_store_dwordx2 v[4:5], v[18:19], off offset:1024
	s_waitcnt vmcnt(3)
	v_lshlrev_b32_e32 v8, 16, v36
	v_and_b32_e32 v9, 0xffff0000, v36
	v_lshlrev_b32_e32 v10, 16, v37
	v_and_b32_e32 v11, 0xffff0000, v37
	v_pk_add_f32 v[8:9], v[88:89], v[8:9]
	v_pk_add_f32 v[10:11], v[90:91], v[10:11]
	v_pk_add_f32 v[8:9], v[92:93], v[8:9]
	v_pk_add_f32 v[10:11], v[94:95], v[10:11]
	v_pk_add_f32 v[8:9], v[96:97], v[8:9]
	v_pk_add_f32 v[10:11], v[98:99], v[10:11]
	v_pk_add_f32 v[8:9], v[100:101], v[8:9]
	v_pk_add_f32 v[10:11], v[102:103], v[10:11]
	v_fmac_f32_e32 v6, v8, v8
	v_fmac_f32_e32 v6, v9, v9
	v_fmac_f32_e32 v6, v10, v10
	v_fmac_f32_e32 v6, v11, v11
	v_cvt_pk_bf16_f32 v20, v8, v9
	v_cvt_pk_bf16_f32 v21, v10, v11
	global_store_dwordx2 v[4:5], v[20:21], off offset:1536
	v_xor_b32_e32 v12, 32, v164
	v_lshlrev_b32_e32 v12, 2, v12
	ds_bpermute_b32 v7, v12, v6
	s_waitcnt lgkmcnt(0)
	v_add_f32_e32 v6, v6, v7
	v_xor_b32_e32 v12, 16, v164
	v_lshlrev_b32_e32 v12, 2, v12
	ds_bpermute_b32 v7, v12, v6
	s_waitcnt lgkmcnt(0)
	v_add_f32_e32 v6, v6, v7
	v_xor_b32_e32 v12, 8, v164
	v_lshlrev_b32_e32 v12, 2, v12
	ds_bpermute_b32 v7, v12, v6
	s_waitcnt lgkmcnt(0)
	v_add_f32_e32 v6, v6, v7
	v_xor_b32_e32 v12, 4, v164
	v_lshlrev_b32_e32 v12, 2, v12
	ds_bpermute_b32 v7, v12, v6
	s_waitcnt lgkmcnt(0)
	v_add_f32_e32 v6, v6, v7
	v_xor_b32_e32 v12, 2, v164
	v_lshlrev_b32_e32 v12, 2, v12
	ds_bpermute_b32 v7, v12, v6
	s_waitcnt lgkmcnt(0)
	v_add_f32_e32 v6, v6, v7
	v_xor_b32_e32 v12, 1, v164
	v_lshlrev_b32_e32 v12, 2, v12
	ds_bpermute_b32 v7, v12, v6
	s_waitcnt lgkmcnt(0)
	s_and_b64 exec, exec, vcc
	s_cbranch_execz .LBB0_64
	v_lshl_add_u64 v[4:5], v[136:137], 2, s[6:7]
	s_waitcnt lgkmcnt(0)
	v_add_f32_e32 v6, v6, v7
	global_store_dword v[4:5], v6, off
	s_branch .LBB0_64

.LBB0_361:
	s_waitcnt vmcnt(0) lgkmcnt(0)
	v_mul_lo_u32 v128, v152, s42
	s_lshl_b32 s18, s47, 8
	v_lshl_add_u32 v129, v146, 1, s18
	v_add_u32_e32 v128, v128, v129
	v_mov_b32_e32 v160, 1.0
	v_mov_b32_e32 v161, 1.0
	v_fmamk_f32 v132, v167, 0x3a800000, v162
	v_cmp_gt_f32_e32 vcc, s40, v132
	v_mul_f32_e32 v133, 0x4b800000, v132
	v_pk_mul_f32 v[116:117], v[124:125], v[116:117]
	v_pk_mul_f32 v[118:119], v[126:127], v[118:119]
	v_cndmask_b32_e32 v132, v132, v133, vcc
	v_rsq_f32_e32 v132, v132
	v_pk_mul_f32 v[112:113], v[120:121], v[112:113]
	v_pk_mul_f32 v[114:115], v[122:123], v[114:115]
	v_mul_f32_e32 v133, 0x45800000, v132
	v_cndmask_b32_e32 v132, v132, v133, vcc
	v_cndmask_b32_e64 v132, v132, 1.0, s[14:15]
	v_mul_f32_e32 v130, 0xbfb8aa3b, v132
	v_mul_f32_e32 v134, v132, v132
	v_pk_mul_f32 v[124:125], v[124:125], v[130:131] op_sel_hi:[1,0]
	v_pk_mul_f32 v[126:127], v[126:127], v[130:131] op_sel_hi:[1,0]
	v_pk_mul_f32 v[120:121], v[120:121], v[130:131] op_sel_hi:[1,0]
	v_pk_mul_f32 v[122:123], v[122:123], v[130:131] op_sel_hi:[1,0]
	v_exp_f32_e32 v124, v124
	v_exp_f32_e32 v125, v125
	v_exp_f32_e32 v126, v126
	v_exp_f32_e32 v127, v127
	v_exp_f32_e32 v120, v120
	v_exp_f32_e32 v121, v121
	v_exp_f32_e32 v122, v122
	v_exp_f32_e32 v123, v123
	v_pk_add_f32 v[124:125], v[124:125], v[160:161]
	v_pk_add_f32 v[126:127], v[126:127], v[160:161]
	v_pk_add_f32 v[120:121], v[120:121], v[160:161]
	v_pk_add_f32 v[122:123], v[122:123], v[160:161]
	v_rcp_f32_e32 v124, v124
	v_rcp_f32_e32 v125, v125
	v_rcp_f32_e32 v126, v126
	v_rcp_f32_e32 v127, v127
	v_rcp_f32_e32 v120, v120
	v_rcp_f32_e32 v121, v121
	v_rcp_f32_e32 v122, v122
	v_rcp_f32_e32 v123, v123
	v_pk_mul_f32 v[116:117], v[116:117], v[134:135] op_sel_hi:[1,0]
	v_pk_mul_f32 v[118:119], v[118:119], v[134:135] op_sel_hi:[1,0]
	v_pk_mul_f32 v[112:113], v[112:113], v[134:135] op_sel_hi:[1,0]
	v_pk_mul_f32 v[114:115], v[114:115], v[134:135] op_sel_hi:[1,0]
	v_pk_mul_f32 v[116:117], v[116:117], v[124:125]
	v_pk_mul_f32 v[118:119], v[118:119], v[126:127]
	v_pk_mul_f32 v[112:113], v[112:113], v[120:121]
	v_pk_mul_f32 v[114:115], v[114:115], v[122:123]
	v_cvt_pk_bf16_f32 v124, v116, v117
	v_cvt_pk_bf16_f32 v125, v118, v119
	v_cvt_pk_bf16_f32 v126, v112, v113
	v_cvt_pk_bf16_f32 v127, v114, v115
	global_store_dwordx4 v128, v[124:127], s[28:29]
	v_fmamk_f32 v132, v168, 0x3a800000, v162
	v_cmp_gt_f32_e32 vcc, s40, v132
	v_mul_f32_e32 v133, 0x4b800000, v132
	v_pk_mul_f32 v[100:101], v[108:109], v[100:101]
	v_pk_mul_f32 v[102:103], v[110:111], v[102:103]
	v_cndmask_b32_e32 v132, v132, v133, vcc
	v_rsq_f32_e32 v132, v132
	v_pk_mul_f32 v[96:97], v[104:105], v[96:97]
	v_pk_mul_f32 v[98:99], v[106:107], v[98:99]
	v_mul_f32_e32 v133, 0x45800000, v132
	v_cndmask_b32_e32 v132, v132, v133, vcc
	v_cndmask_b32_e64 v132, v132, 1.0, s[14:15]
	v_mul_f32_e32 v130, 0xbfb8aa3b, v132
	v_mul_f32_e32 v134, v132, v132
	v_pk_mul_f32 v[108:109], v[108:109], v[130:131] op_sel_hi:[1,0]
	v_pk_mul_f32 v[110:111], v[110:111], v[130:131] op_sel_hi:[1,0]
	v_pk_mul_f32 v[104:105], v[104:105], v[130:131] op_sel_hi:[1,0]
	v_pk_mul_f32 v[106:107], v[106:107], v[130:131] op_sel_hi:[1,0]
	v_exp_f32_e32 v108, v108
	v_exp_f32_e32 v109, v109
	v_exp_f32_e32 v110, v110
	v_exp_f32_e32 v111, v111
	v_exp_f32_e32 v104, v104
	v_exp_f32_e32 v105, v105
	v_exp_f32_e32 v106, v106
	v_exp_f32_e32 v107, v107
	v_pk_add_f32 v[108:109], v[108:109], v[160:161]
	v_pk_add_f32 v[110:111], v[110:111], v[160:161]
	v_pk_add_f32 v[104:105], v[104:105], v[160:161]
	v_pk_add_f32 v[106:107], v[106:107], v[160:161]
	v_rcp_f32_e32 v108, v108
	v_rcp_f32_e32 v109, v109
	v_rcp_f32_e32 v110, v110
	v_rcp_f32_e32 v111, v111
	v_rcp_f32_e32 v104, v104
	v_rcp_f32_e32 v105, v105
	v_rcp_f32_e32 v106, v106
	v_rcp_f32_e32 v107, v107
	v_pk_mul_f32 v[100:101], v[100:101], v[134:135] op_sel_hi:[1,0]
	v_pk_mul_f32 v[102:103], v[102:103], v[134:135] op_sel_hi:[1,0]
	v_pk_mul_f32 v[96:97], v[96:97], v[134:135] op_sel_hi:[1,0]
	v_pk_mul_f32 v[98:99], v[98:99], v[134:135] op_sel_hi:[1,0]
	v_pk_mul_f32 v[100:101], v[100:101], v[108:109]
	v_pk_mul_f32 v[102:103], v[102:103], v[110:111]
	v_pk_mul_f32 v[96:97], v[96:97], v[104:105]
	v_pk_mul_f32 v[98:99], v[98:99], v[106:107]
	v_add_u32_e32 v129, 0x16000, v128
	v_cvt_pk_bf16_f32 v108, v100, v101
	v_cvt_pk_bf16_f32 v109, v102, v103
	v_cvt_pk_bf16_f32 v110, v96, v97
	v_cvt_pk_bf16_f32 v111, v98, v99
	global_store_dwordx4 v129, v[108:111], s[28:29]
	v_fmamk_f32 v132, v169, 0x3a800000, v162
	v_cmp_gt_f32_e32 vcc, s40, v132
	v_mul_f32_e32 v133, 0x4b800000, v132
	v_pk_mul_f32 v[84:85], v[92:93], v[84:85]
	v_pk_mul_f32 v[86:87], v[94:95], v[86:87]
	v_cndmask_b32_e32 v132, v132, v133, vcc
	v_rsq_f32_e32 v132, v132
	v_pk_mul_f32 v[80:81], v[88:89], v[80:81]
	v_pk_mul_f32 v[82:83], v[90:91], v[82:83]
	v_mul_f32_e32 v133, 0x45800000, v132
	v_cndmask_b32_e32 v132, v132, v133, vcc
	v_cndmask_b32_e64 v132, v132, 1.0, s[14:15]
	v_mul_f32_e32 v130, 0xbfb8aa3b, v132
	v_mul_f32_e32 v134, v132, v132
	v_pk_mul_f32 v[92:93], v[92:93], v[130:131] op_sel_hi:[1,0]
	v_pk_mul_f32 v[94:95], v[94:95], v[130:131] op_sel_hi:[1,0]
	v_pk_mul_f32 v[88:89], v[88:89], v[130:131] op_sel_hi:[1,0]
	v_pk_mul_f32 v[90:91], v[90:91], v[130:131] op_sel_hi:[1,0]
	v_exp_f32_e32 v92, v92
	v_exp_f32_e32 v93, v93
	v_exp_f32_e32 v94, v94
	v_exp_f32_e32 v95, v95
	v_exp_f32_e32 v88, v88
	v_exp_f32_e32 v89, v89
	v_exp_f32_e32 v90, v90
	v_exp_f32_e32 v91, v91
	v_pk_add_f32 v[92:93], v[92:93], v[160:161]
	v_pk_add_f32 v[94:95], v[94:95], v[160:161]
	v_pk_add_f32 v[88:89], v[88:89], v[160:161]
	v_pk_add_f32 v[90:91], v[90:91], v[160:161]
	v_rcp_f32_e32 v92, v92
	v_rcp_f32_e32 v93, v93
	v_rcp_f32_e32 v94, v94
	v_rcp_f32_e32 v95, v95
	v_rcp_f32_e32 v88, v88
	v_rcp_f32_e32 v89, v89
	v_rcp_f32_e32 v90, v90
	v_rcp_f32_e32 v91, v91
	v_pk_mul_f32 v[84:85], v[84:85], v[134:135] op_sel_hi:[1,0]
	v_pk_mul_f32 v[86:87], v[86:87], v[134:135] op_sel_hi:[1,0]
	v_pk_mul_f32 v[80:81], v[80:81], v[134:135] op_sel_hi:[1,0]
	v_pk_mul_f32 v[82:83], v[82:83], v[134:135] op_sel_hi:[1,0]
	v_pk_mul_f32 v[84:85], v[84:85], v[92:93]
	v_pk_mul_f32 v[86:87], v[86:87], v[94:95]
	v_pk_mul_f32 v[80:81], v[80:81], v[88:89]
	v_pk_mul_f32 v[82:83], v[82:83], v[90:91]
	v_add_u32_e32 v129, 0x2c000, v128
	v_cvt_pk_bf16_f32 v92, v84, v85
	v_cvt_pk_bf16_f32 v93, v86, v87
	v_cvt_pk_bf16_f32 v94, v80, v81
	v_cvt_pk_bf16_f32 v95, v82, v83
	global_store_dwordx4 v129, v[92:95], s[28:29]
	v_fmamk_f32 v132, v170, 0x3a800000, v162
	v_cmp_gt_f32_e32 vcc, s40, v132
	v_mul_f32_e32 v133, 0x4b800000, v132
	v_pk_mul_f32 v[68:69], v[76:77], v[68:69]
	v_pk_mul_f32 v[70:71], v[78:79], v[70:71]
	v_cndmask_b32_e32 v132, v132, v133, vcc
	v_rsq_f32_e32 v132, v132
	v_pk_mul_f32 v[64:65], v[72:73], v[64:65]
	v_pk_mul_f32 v[66:67], v[74:75], v[66:67]
	v_mul_f32_e32 v133, 0x45800000, v132
	v_cndmask_b32_e32 v132, v132, v133, vcc
	v_cndmask_b32_e64 v132, v132, 1.0, s[14:15]
	v_mul_f32_e32 v130, 0xbfb8aa3b, v132
	v_mul_f32_e32 v134, v132, v132
	v_pk_mul_f32 v[76:77], v[76:77], v[130:131] op_sel_hi:[1,0]
	v_pk_mul_f32 v[78:79], v[78:79], v[130:131] op_sel_hi:[1,0]
	v_pk_mul_f32 v[72:73], v[72:73], v[130:131] op_sel_hi:[1,0]
	v_pk_mul_f32 v[74:75], v[74:75], v[130:131] op_sel_hi:[1,0]
	v_exp_f32_e32 v76, v76
	v_exp_f32_e32 v77, v77
	v_exp_f32_e32 v78, v78
	v_exp_f32_e32 v79, v79
	v_exp_f32_e32 v72, v72
	v_exp_f32_e32 v73, v73
	v_exp_f32_e32 v74, v74
	v_exp_f32_e32 v75, v75
	v_pk_add_f32 v[76:77], v[76:77], v[160:161]
	v_pk_add_f32 v[78:79], v[78:79], v[160:161]
	v_pk_add_f32 v[72:73], v[72:73], v[160:161]
	v_pk_add_f32 v[74:75], v[74:75], v[160:161]
	v_rcp_f32_e32 v76, v76
	v_rcp_f32_e32 v77, v77
	v_rcp_f32_e32 v78, v78
	v_rcp_f32_e32 v79, v79
	v_rcp_f32_e32 v72, v72
	v_rcp_f32_e32 v73, v73
	v_rcp_f32_e32 v74, v74
	v_rcp_f32_e32 v75, v75
	v_pk_mul_f32 v[68:69], v[68:69], v[134:135] op_sel_hi:[1,0]
	v_pk_mul_f32 v[70:71], v[70:71], v[134:135] op_sel_hi:[1,0]
	v_pk_mul_f32 v[64:65], v[64:65], v[134:135] op_sel_hi:[1,0]
	v_pk_mul_f32 v[66:67], v[66:67], v[134:135] op_sel_hi:[1,0]
	v_pk_mul_f32 v[68:69], v[68:69], v[76:77]
	v_pk_mul_f32 v[70:71], v[70:71], v[78:79]
	v_pk_mul_f32 v[64:65], v[64:65], v[72:73]
	v_pk_mul_f32 v[66:67], v[66:67], v[74:75]
	v_add_u32_e32 v129, 0x42000, v128
	v_cvt_pk_bf16_f32 v76, v68, v69
	v_cvt_pk_bf16_f32 v77, v70, v71
	v_cvt_pk_bf16_f32 v78, v64, v65
	v_cvt_pk_bf16_f32 v79, v66, v67
	global_store_dwordx4 v129, v[76:79], s[28:29]
	v_fmamk_f32 v132, v171, 0x3a800000, v162
	v_cmp_gt_f32_e32 vcc, s40, v132
	v_mul_f32_e32 v133, 0x4b800000, v132
	v_pk_mul_f32 v[52:53], v[60:61], v[52:53]
	v_pk_mul_f32 v[54:55], v[62:63], v[54:55]
	v_cndmask_b32_e32 v132, v132, v133, vcc
	v_rsq_f32_e32 v132, v132
	v_pk_mul_f32 v[48:49], v[56:57], v[48:49]
	v_pk_mul_f32 v[50:51], v[58:59], v[50:51]
	v_mul_f32_e32 v133, 0x45800000, v132
	v_cndmask_b32_e32 v132, v132, v133, vcc
	v_cndmask_b32_e64 v132, v132, 1.0, s[14:15]
	v_mul_f32_e32 v130, 0xbfb8aa3b, v132
	v_mul_f32_e32 v134, v132, v132
	v_pk_mul_f32 v[60:61], v[60:61], v[130:131] op_sel_hi:[1,0]
	v_pk_mul_f32 v[62:63], v[62:63], v[130:131] op_sel_hi:[1,0]
	v_pk_mul_f32 v[56:57], v[56:57], v[130:131] op_sel_hi:[1,0]
	v_pk_mul_f32 v[58:59], v[58:59], v[130:131] op_sel_hi:[1,0]
	v_exp_f32_e32 v60, v60
	v_exp_f32_e32 v61, v61
	v_exp_f32_e32 v62, v62
	v_exp_f32_e32 v63, v63
	v_exp_f32_e32 v56, v56
	v_exp_f32_e32 v57, v57
	v_exp_f32_e32 v58, v58
	v_exp_f32_e32 v59, v59
	v_pk_add_f32 v[60:61], v[60:61], v[160:161]
	v_pk_add_f32 v[62:63], v[62:63], v[160:161]
	v_pk_add_f32 v[56:57], v[56:57], v[160:161]
	v_pk_add_f32 v[58:59], v[58:59], v[160:161]
	v_rcp_f32_e32 v60, v60
	v_rcp_f32_e32 v61, v61
	v_rcp_f32_e32 v62, v62
	v_rcp_f32_e32 v63, v63
	v_rcp_f32_e32 v56, v56
	v_rcp_f32_e32 v57, v57
	v_rcp_f32_e32 v58, v58
	v_rcp_f32_e32 v59, v59
	v_pk_mul_f32 v[52:53], v[52:53], v[134:135] op_sel_hi:[1,0]
	v_pk_mul_f32 v[54:55], v[54:55], v[134:135] op_sel_hi:[1,0]
	v_pk_mul_f32 v[48:49], v[48:49], v[134:135] op_sel_hi:[1,0]
	v_pk_mul_f32 v[50:51], v[50:51], v[134:135] op_sel_hi:[1,0]
	v_pk_mul_f32 v[52:53], v[52:53], v[60:61]
	v_pk_mul_f32 v[54:55], v[54:55], v[62:63]
	v_pk_mul_f32 v[48:49], v[48:49], v[56:57]
	v_pk_mul_f32 v[50:51], v[50:51], v[58:59]
	v_add_u32_e32 v129, 0xb0000, v128
	v_cvt_pk_bf16_f32 v60, v52, v53
	v_cvt_pk_bf16_f32 v61, v54, v55
	v_cvt_pk_bf16_f32 v62, v48, v49
	v_cvt_pk_bf16_f32 v63, v50, v51
	global_store_dwordx4 v129, v[60:63], s[28:29]
	v_fmamk_f32 v132, v172, 0x3a800000, v162
	v_cmp_gt_f32_e32 vcc, s40, v132
	v_mul_f32_e32 v133, 0x4b800000, v132
	v_pk_mul_f32 v[36:37], v[44:45], v[36:37]
	v_pk_mul_f32 v[38:39], v[46:47], v[38:39]
	v_cndmask_b32_e32 v132, v132, v133, vcc
	v_rsq_f32_e32 v132, v132
	v_pk_mul_f32 v[32:33], v[40:41], v[32:33]
	v_pk_mul_f32 v[34:35], v[42:43], v[34:35]
	v_mul_f32_e32 v133, 0x45800000, v132
	v_cndmask_b32_e32 v132, v132, v133, vcc
	v_cndmask_b32_e64 v132, v132, 1.0, s[14:15]
	v_mul_f32_e32 v130, 0xbfb8aa3b, v132
	v_mul_f32_e32 v134, v132, v132
	v_pk_mul_f32 v[44:45], v[44:45], v[130:131] op_sel_hi:[1,0]
	v_pk_mul_f32 v[46:47], v[46:47], v[130:131] op_sel_hi:[1,0]
	v_pk_mul_f32 v[40:41], v[40:41], v[130:131] op_sel_hi:[1,0]
	v_pk_mul_f32 v[42:43], v[42:43], v[130:131] op_sel_hi:[1,0]
	v_exp_f32_e32 v44, v44
	v_exp_f32_e32 v45, v45
	v_exp_f32_e32 v46, v46
	v_exp_f32_e32 v47, v47
	v_exp_f32_e32 v40, v40
	v_exp_f32_e32 v41, v41
	v_exp_f32_e32 v42, v42
	v_exp_f32_e32 v43, v43
	v_pk_add_f32 v[44:45], v[44:45], v[160:161]
	v_pk_add_f32 v[46:47], v[46:47], v[160:161]
	v_pk_add_f32 v[40:41], v[40:41], v[160:161]
	v_pk_add_f32 v[42:43], v[42:43], v[160:161]
	v_rcp_f32_e32 v44, v44
	v_rcp_f32_e32 v45, v45
	v_rcp_f32_e32 v46, v46
	v_rcp_f32_e32 v47, v47
	v_rcp_f32_e32 v40, v40
	v_rcp_f32_e32 v41, v41
	v_rcp_f32_e32 v42, v42
	v_rcp_f32_e32 v43, v43
	v_pk_mul_f32 v[36:37], v[36:37], v[134:135] op_sel_hi:[1,0]
	v_pk_mul_f32 v[38:39], v[38:39], v[134:135] op_sel_hi:[1,0]
	v_pk_mul_f32 v[32:33], v[32:33], v[134:135] op_sel_hi:[1,0]
	v_pk_mul_f32 v[34:35], v[34:35], v[134:135] op_sel_hi:[1,0]
	v_pk_mul_f32 v[36:37], v[36:37], v[44:45]
	v_pk_mul_f32 v[38:39], v[38:39], v[46:47]
	v_pk_mul_f32 v[32:33], v[32:33], v[40:41]
	v_pk_mul_f32 v[34:35], v[34:35], v[42:43]
	v_add_u32_e32 v129, 0xc6000, v128
	v_cvt_pk_bf16_f32 v44, v36, v37
	v_cvt_pk_bf16_f32 v45, v38, v39
	v_cvt_pk_bf16_f32 v46, v32, v33
	v_cvt_pk_bf16_f32 v47, v34, v35
	global_store_dwordx4 v129, v[44:47], s[28:29]
	v_fmamk_f32 v132, v174, 0x3a800000, v162
	v_cmp_gt_f32_e32 vcc, s40, v132
	v_mul_f32_e32 v133, 0x4b800000, v132
	v_pk_mul_f32 v[20:21], v[28:29], v[20:21]
	v_pk_mul_f32 v[22:23], v[30:31], v[22:23]
	v_cndmask_b32_e32 v132, v132, v133, vcc
	v_rsq_f32_e32 v132, v132
	v_pk_mul_f32 v[16:17], v[24:25], v[16:17]
	v_pk_mul_f32 v[18:19], v[26:27], v[18:19]
	v_mul_f32_e32 v133, 0x45800000, v132
	v_cndmask_b32_e32 v132, v132, v133, vcc
	v_cndmask_b32_e64 v132, v132, 1.0, s[14:15]
	v_mul_f32_e32 v130, 0xbfb8aa3b, v132
	v_mul_f32_e32 v134, v132, v132
	v_pk_mul_f32 v[28:29], v[28:29], v[130:131] op_sel_hi:[1,0]
	v_pk_mul_f32 v[30:31], v[30:31], v[130:131] op_sel_hi:[1,0]
	v_pk_mul_f32 v[24:25], v[24:25], v[130:131] op_sel_hi:[1,0]
	v_pk_mul_f32 v[26:27], v[26:27], v[130:131] op_sel_hi:[1,0]
	v_exp_f32_e32 v28, v28
	v_exp_f32_e32 v29, v29
	v_exp_f32_e32 v30, v30
	v_exp_f32_e32 v31, v31
	v_exp_f32_e32 v24, v24
	v_exp_f32_e32 v25, v25
	v_exp_f32_e32 v26, v26
	v_exp_f32_e32 v27, v27
	v_pk_add_f32 v[28:29], v[28:29], v[160:161]
	v_pk_add_f32 v[30:31], v[30:31], v[160:161]
	v_pk_add_f32 v[24:25], v[24:25], v[160:161]
	v_pk_add_f32 v[26:27], v[26:27], v[160:161]
	v_rcp_f32_e32 v28, v28
	v_rcp_f32_e32 v29, v29
	v_rcp_f32_e32 v30, v30
	v_rcp_f32_e32 v31, v31
	v_rcp_f32_e32 v24, v24
	v_rcp_f32_e32 v25, v25
	v_rcp_f32_e32 v26, v26
	v_rcp_f32_e32 v27, v27
	v_pk_mul_f32 v[20:21], v[20:21], v[134:135] op_sel_hi:[1,0]
	v_pk_mul_f32 v[22:23], v[22:23], v[134:135] op_sel_hi:[1,0]
	v_pk_mul_f32 v[16:17], v[16:17], v[134:135] op_sel_hi:[1,0]
	v_pk_mul_f32 v[18:19], v[18:19], v[134:135] op_sel_hi:[1,0]
	v_pk_mul_f32 v[20:21], v[20:21], v[28:29]
	v_pk_mul_f32 v[22:23], v[22:23], v[30:31]
	v_pk_mul_f32 v[16:17], v[16:17], v[24:25]
	v_pk_mul_f32 v[18:19], v[18:19], v[26:27]
	v_add_u32_e32 v129, 0xdc000, v128
	v_cvt_pk_bf16_f32 v28, v20, v21
	v_cvt_pk_bf16_f32 v29, v22, v23
	v_cvt_pk_bf16_f32 v30, v16, v17
	v_cvt_pk_bf16_f32 v31, v18, v19
	global_store_dwordx4 v129, v[28:31], s[28:29]
	v_fmamk_f32 v132, v173, 0x3a800000, v162
	v_cmp_gt_f32_e32 vcc, s40, v132
	v_mul_f32_e32 v133, 0x4b800000, v132
	v_pk_mul_f32 v[4:5], v[12:13], v[4:5]
	v_pk_mul_f32 v[6:7], v[14:15], v[6:7]
	v_cndmask_b32_e32 v132, v132, v133, vcc
	v_rsq_f32_e32 v132, v132
	v_pk_mul_f32 v[0:1], v[8:9], v[0:1]
	v_pk_mul_f32 v[2:3], v[10:11], v[2:3]
	v_mul_f32_e32 v133, 0x45800000, v132
	v_cndmask_b32_e32 v132, v132, v133, vcc
	v_cndmask_b32_e64 v132, v132, 1.0, s[14:15]
	v_mul_f32_e32 v130, 0xbfb8aa3b, v132
	v_mul_f32_e32 v134, v132, v132
	v_pk_mul_f32 v[12:13], v[12:13], v[130:131] op_sel_hi:[1,0]
	v_pk_mul_f32 v[14:15], v[14:15], v[130:131] op_sel_hi:[1,0]
	v_pk_mul_f32 v[8:9], v[8:9], v[130:131] op_sel_hi:[1,0]
	v_pk_mul_f32 v[10:11], v[10:11], v[130:131] op_sel_hi:[1,0]
	v_exp_f32_e32 v12, v12
	v_exp_f32_e32 v13, v13
	v_exp_f32_e32 v14, v14
	v_exp_f32_e32 v15, v15
	v_exp_f32_e32 v8, v8
	v_exp_f32_e32 v9, v9
	v_exp_f32_e32 v10, v10
	v_exp_f32_e32 v11, v11
	v_pk_add_f32 v[12:13], v[12:13], v[160:161]
	v_pk_add_f32 v[14:15], v[14:15], v[160:161]
	v_pk_add_f32 v[8:9], v[8:9], v[160:161]
	v_pk_add_f32 v[10:11], v[10:11], v[160:161]
	v_rcp_f32_e32 v12, v12
	v_rcp_f32_e32 v13, v13
	v_rcp_f32_e32 v14, v14
	v_rcp_f32_e32 v15, v15
	v_rcp_f32_e32 v8, v8
	v_rcp_f32_e32 v9, v9
	v_rcp_f32_e32 v10, v10
	v_rcp_f32_e32 v11, v11
	v_pk_mul_f32 v[4:5], v[4:5], v[134:135] op_sel_hi:[1,0]
	v_pk_mul_f32 v[6:7], v[6:7], v[134:135] op_sel_hi:[1,0]
	v_pk_mul_f32 v[0:1], v[0:1], v[134:135] op_sel_hi:[1,0]
	v_pk_mul_f32 v[2:3], v[2:3], v[134:135] op_sel_hi:[1,0]
	v_pk_mul_f32 v[4:5], v[4:5], v[12:13]
	v_pk_mul_f32 v[6:7], v[6:7], v[14:15]
	v_pk_mul_f32 v[0:1], v[0:1], v[8:9]
	v_pk_mul_f32 v[2:3], v[2:3], v[10:11]
	v_add_u32_e32 v129, 0xf2000, v128
	v_cvt_pk_bf16_f32 v12, v4, v5
	v_cvt_pk_bf16_f32 v13, v6, v7
	v_cvt_pk_bf16_f32 v14, v0, v1
	v_cvt_pk_bf16_f32 v15, v2, v3
	global_store_dwordx4 v129, v[12:15], s[28:29]
	s_and_b64 vcc, exec, s[38:39]
	s_cbranch_vccz .LBB0_158

.LBB0_632:
	v_mov_b32_e32 v0, v147
	v_readlane_b32 s6, v243, 24
	v_ashrrev_i32_e32 v1, 6, v0
	s_nop 0
	v_add_u32_e32 v16, s6, v1
	v_cmp_gt_i32_e32 vcc, s28, v16
	s_and_saveexec_b64 s[6:7], vcc
	s_cbranch_execz .LBB0_628
	v_and_b32_e32 v2, 64, v164
	v_add_u32_e32 v2, 64, v2
	v_xor_b32_e32 v3, 32, v164
	v_cmp_lt_i32_e32 vcc, v3, v2
	v_and_b32_e32 v1, 63, v0
	s_cmp_lg_u64 s[12:13], 0
	v_cndmask_b32_e32 v3, v164, v3, vcc
	v_lshlrev_b32_e32 v31, 2, v3
	v_xor_b32_e32 v3, 16, v164
	v_cmp_lt_i32_e32 vcc, v3, v2
	s_cselect_b64 s[10:11], -1, 0
	v_lshlrev_b32_e32 v136, 3, v1
	v_cndmask_b32_e32 v3, v164, v3, vcc
	v_lshlrev_b32_e32 v32, 2, v3
	v_xor_b32_e32 v3, 8, v164
	v_cmp_lt_i32_e32 vcc, v3, v2
	s_cmp_lg_u64 s[0:1], 0
	v_lshl_add_u64 v[18:19], s[12:13], 0, v[136:137]
	v_cndmask_b32_e32 v3, v164, v3, vcc
	v_lshlrev_b32_e32 v33, 2, v3
	v_xor_b32_e32 v3, 4, v164
	v_cmp_lt_i32_e32 vcc, v3, v2
	s_cselect_b64 s[12:13], -1, 0
	s_cmp_lg_u64 s[14:15], 0
	v_cndmask_b32_e32 v3, v164, v3, vcc
	v_lshlrev_b32_e32 v34, 2, v3
	v_xor_b32_e32 v3, 2, v164
	v_cmp_lt_i32_e32 vcc, v3, v2
	v_lshl_add_u64 v[20:21], s[14:15], 0, v[136:137]
	s_cselect_b64 s[14:15], -1, 0
	v_cndmask_b32_e32 v3, v164, v3, vcc
	v_lshlrev_b32_e32 v35, 2, v3
	v_xor_b32_e32 v3, 1, v164
	v_cmp_lt_i32_e32 vcc, v3, v2
	s_cmp_lg_u64 s[18:19], 0
	v_lshlrev_b32_e32 v0, 2, v1
	v_cndmask_b32_e32 v2, v164, v3, vcc
	v_lshlrev_b32_e32 v36, 2, v2
	v_lshlrev_b32_e32 v2, 4, v1
	v_mov_b32_e32 v3, v137
	v_lshl_add_u64 v[22:23], s[16:17], 0, v[2:3]
	s_cselect_b64 s[16:17], -1, 0
	s_cmp_lg_u64 s[24:25], 0
	s_mov_b64 s[8:9], 0
	v_cmp_eq_u32_e64 s[38:39], 0, v1
	v_lshl_add_u64 v[24:25], s[20:21], 0, v[2:3]
	v_lshl_add_u64 v[26:27], s[18:19], 0, v[136:137]
	s_cselect_b64 s[18:19], -1, 0
	v_lshl_add_u64 v[28:29], s[24:25], 0, v[2:3]
	s_sub_i32 s24, 0, s29
	v_lshlrev_b32_e32 v136, 2, v0
	s_and_b64 vcc, exec, s[12:13]
	s_cbranch_vccnz .Lnorm_pre_done
	global_load_dwordx4 v[60:63], v[22:23], off
	global_load_dwordx4 v[64:67], v[22:23], off offset:1024
	global_load_dwordx4 v[68:71], v[22:23], off offset:2048
	global_load_dwordx4 v[72:75], v[22:23], off offset:3072
	s_andn2_b64 vcc, exec, s[16:17]
	s_cbranch_vccnz .Lnorm_pre_done
	global_load_dwordx4 v[76:79], v[24:25], off
	global_load_dwordx4 v[80:83], v[24:25], off offset:1024
	global_load_dwordx4 v[84:87], v[24:25], off offset:2048
	global_load_dwordx4 v[88:91], v[24:25], off offset:3072
.Lnorm_pre_done:
	s_branch .LBB0_635
.LBB0_634:
	v_add_u32_e32 v16, s99, v16
	v_cmp_le_i32_e32 vcc, s28, v16
	s_or_b64 s[8:9], vcc, s[8:9]
	s_andn2_b64 exec, exec, s[8:9]
	s_cbranch_execz .LBB0_628

.LBB0_643:
	s_cbranch_execz .LBB0_634
	v_fmamk_f32 v30, v30, 0x3a800000, v162
	v_mul_f32_e32 v37, 0x4b800000, v30
	v_cmp_gt_f32_e32 vcc, s40, v30
	s_nop 1
	v_cndmask_b32_e32 v30, v30, v37, vcc
	v_rsq_f32_e32 v30, v30
	s_nop 0
	v_mul_f32_e32 v37, 0x45800000, v30
	v_cndmask_b32_e32 v30, v30, v37, vcc
	s_andn2_b64 vcc, exec, s[14:15]
	v_mul_f32_e32 v51, v12, v30
	v_mul_f32_e32 v52, v13, v30
	v_mul_f32_e32 v49, v14, v30
	v_mul_f32_e32 v50, v15, v30
	v_mul_f32_e32 v47, v8, v30
	v_mul_f32_e32 v48, v9, v30
	v_mul_f32_e32 v45, v10, v30
	v_mul_f32_e32 v46, v11, v30
	v_mul_f32_e32 v43, v4, v30
	v_mul_f32_e32 v44, v5, v30
	v_mul_f32_e32 v41, v6, v30
	v_mul_f32_e32 v42, v7, v30
	v_mul_f32_e32 v39, v0, v30
	v_mul_f32_e32 v40, v1, v30
	v_mul_f32_e32 v37, v2, v30
	v_mul_f32_e32 v38, v3, v30
	s_cbranch_vccnz .LBB0_646
	v_lshlrev_b64 v[58:59], 11, v[16:17]
	v_lshl_add_u64 v[58:59], v[20:21], 0, v[58:59]
	v_mul_f32_e32 v53, v51, v60
	v_mul_f32_e32 v54, v52, v61
	v_mul_f32_e32 v55, v49, v62
	v_mul_f32_e32 v56, v50, v63
	v_cvt_pk_bf16_f32 v54, v53, v54
	v_cvt_pk_bf16_f32 v55, v55, v56
	global_store_dwordx2 v[58:59], v[54:55], off
	s_nop 1
	v_mul_f32_e32 v53, v47, v64
	v_mul_f32_e32 v54, v48, v65
	v_mul_f32_e32 v55, v45, v66
	v_mul_f32_e32 v56, v46, v67
	v_cvt_pk_bf16_f32 v54, v53, v54
	v_cvt_pk_bf16_f32 v55, v55, v56
	global_store_dwordx2 v[58:59], v[54:55], off offset:512
	s_nop 1
	v_mul_f32_e32 v53, v43, v68
	v_mul_f32_e32 v54, v44, v69
	v_mul_f32_e32 v55, v41, v70
	v_mul_f32_e32 v56, v42, v71
	v_cvt_pk_bf16_f32 v54, v53, v54
	v_cvt_pk_bf16_f32 v55, v55, v56
	global_store_dwordx2 v[58:59], v[54:55], off offset:1024
	s_nop 1
	v_mul_f32_e32 v53, v39, v72
	v_mul_f32_e32 v54, v40, v73
	v_mul_f32_e32 v55, v37, v74
	v_mul_f32_e32 v56, v38, v75
	v_cvt_pk_bf16_f32 v54, v53, v54
	v_cvt_pk_bf16_f32 v55, v55, v56
	global_store_dwordx2 v[58:59], v[54:55], off offset:1536
	s_nop 1
.LBB0_646:
	s_andn2_b64 vcc, exec, s[16:17]
	s_cbranch_vccnz .LBB0_648
	v_lshlrev_b64 v[58:59], 11, v[16:17]
	v_lshl_add_u64 v[58:59], v[26:27], 0, v[58:59]
	v_mul_f32_e32 v53, v51, v76
	v_mul_f32_e32 v54, v52, v77
	v_mul_f32_e32 v55, v49, v78
	v_mul_f32_e32 v56, v50, v79
	v_cvt_pk_bf16_f32 v54, v53, v54
	v_cvt_pk_bf16_f32 v55, v55, v56
	global_store_dwordx2 v[58:59], v[54:55], off
	s_nop 1
	v_mul_f32_e32 v53, v47, v80
	v_mul_f32_e32 v54, v48, v81
	v_mul_f32_e32 v55, v45, v82
	v_mul_f32_e32 v56, v46, v83
	v_cvt_pk_bf16_f32 v54, v53, v54
	v_cvt_pk_bf16_f32 v55, v55, v56
	global_store_dwordx2 v[58:59], v[54:55], off offset:512
	s_nop 1
	v_mul_f32_e32 v53, v43, v84
	v_mul_f32_e32 v54, v44, v85
	v_mul_f32_e32 v55, v41, v86
	v_mul_f32_e32 v56, v42, v87
	v_cvt_pk_bf16_f32 v54, v53, v54
	v_cvt_pk_bf16_f32 v55, v55, v56
	global_store_dwordx2 v[58:59], v[54:55], off offset:1024
	s_nop 1
	v_mul_f32_e32 v53, v39, v88
	v_mul_f32_e32 v54, v40, v89
	v_mul_f32_e32 v55, v37, v90
	v_mul_f32_e32 v56, v38, v91
	v_cvt_pk_bf16_f32 v54, v53, v54
	v_cvt_pk_bf16_f32 v55, v55, v56
	global_store_dwordx2 v[58:59], v[54:55], off offset:1536
	s_nop 1
.LBB0_648:
	s_andn2_b64 vcc, exec, s[18:19]
	s_cbranch_vccnz .LBB0_634
	v_lshlrev_b64 v[42:43], 12, v[16:17]
	v_lshl_add_u64 v[42:43], v[28:29], 0, v[42:43]
	v_pk_mul_f32 v[14:15], v[14:15], v[30:31] op_sel_hi:[1,0]
	v_pk_mul_f32 v[12:13], v[12:13], v[30:31] op_sel_hi:[1,0]
	v_pk_mul_f32 v[10:11], v[10:11], v[30:31] op_sel_hi:[1,0]
	v_pk_mul_f32 v[8:9], v[8:9], v[30:31] op_sel_hi:[1,0]
	v_pk_mul_f32 v[6:7], v[6:7], v[30:31] op_sel_hi:[1,0]
	v_pk_mul_f32 v[4:5], v[4:5], v[30:31] op_sel_hi:[1,0]
	v_pk_mul_f32 v[2:3], v[2:3], v[30:31] op_sel_hi:[1,0]
	v_pk_mul_f32 v[0:1], v[0:1], v[30:31] op_sel_hi:[1,0]
	v_pk_mul_f32 v[12:13], v[12:13], v[60:61]
	v_pk_mul_f32 v[14:15], v[14:15], v[62:63]
	global_store_dwordx4 v[42:43], v[12:15], off
	v_pk_mul_f32 v[8:9], v[8:9], v[64:65]
	v_pk_mul_f32 v[10:11], v[10:11], v[66:67]
	global_store_dwordx4 v[42:43], v[8:11], off offset:1024
	v_pk_mul_f32 v[4:5], v[4:5], v[68:69]
	v_pk_mul_f32 v[6:7], v[6:7], v[70:71]
	global_store_dwordx4 v[42:43], v[4:7], off offset:2048
	v_pk_mul_f32 v[0:1], v[0:1], v[72:73]
	v_pk_mul_f32 v[2:3], v[2:3], v[74:75]
	global_store_dwordx4 v[42:43], v[0:3], off offset:3072
	s_nop 1
	s_branch .LBB0_634
